# prompt select scoring: 4-deep key-tile prefetch, scalar loop control, fma chains for the head-weighted relu sum
# speedup vs baseline: 1.2654x; 1.0119x over previous
.Lsel_blk0:
	s_waitcnt vmcnt(6)
	v_mfma_f32_32x32x16_bf16 v[0:15], v[18:21], v[136:139], 0
	v_mfma_f32_32x32x16_bf16 v[0:15], v[22:25], v[140:143], v[0:15]
	v_min_u32_e32 v168, s7, v170
	v_lshlrev_b32_e32 v168, 6, v168
	v_lshl_add_u64 v[134:135], v[44:45], 0, v[168:169]
	global_load_dwordx4 v[136:139], v[134:135], off
	global_load_dwordx4 v[140:143], v[134:135], off offset:32
	v_add_u32_e32 v170, 0x80, v170
	v_cmp_gt_u32_e32 vcc, s72, v49
	s_nop 4
	s_and_saveexec_b64 s[4:5], vcc
	v_max_f32_e32 v0, 0, v0
	v_max_f32_e32 v8, 0, v8
	v_max_f32_e32 v1, 0, v1
	v_max_f32_e32 v9, 0, v9
	v_max_f32_e32 v2, 0, v2
	v_max_f32_e32 v10, 0, v10
	v_max_f32_e32 v3, 0, v3
	v_max_f32_e32 v11, 0, v11
	v_max_f32_e32 v4, 0, v4
	v_max_f32_e32 v12, 0, v12
	v_max_f32_e32 v5, 0, v5
	v_max_f32_e32 v13, 0, v13
	v_max_f32_e32 v6, 0, v6
	v_max_f32_e32 v14, 0, v14
	v_max_f32_e32 v7, 0, v7
	v_max_f32_e32 v15, 0, v15
	v_mul_f32_e32 v53, v38, v0
	v_mul_f32_e32 v52, v30, v8
	v_fmac_f32_e32 v53, v39, v1
	v_fmac_f32_e32 v52, v31, v9
	v_fmac_f32_e32 v53, v40, v2
	v_fmac_f32_e32 v52, v32, v10
	v_fmac_f32_e32 v53, v41, v3
	v_fmac_f32_e32 v52, v33, v11
	v_fmac_f32_e32 v53, v34, v4
	v_fmac_f32_e32 v52, v26, v12
	v_fmac_f32_e32 v53, v35, v5
	v_fmac_f32_e32 v52, v27, v13
	v_fmac_f32_e32 v53, v36, v6
	v_fmac_f32_e32 v52, v28, v14
	v_fma_f32 v1, v37, v7, v53
	v_fma_f32 v0, v29, v15, v52
	s_nop 0
	v_or_b32_e32 v2, 0x80000000, v1
	v_not_b32_e32 v3, v1
	v_cmp_gt_i32_e32 vcc, 0, v1
	s_nop 1
	v_cndmask_b32_e32 v1, v2, v3, vcc
	v_or_b32_e32 v2, 0x80000000, v0
	v_not_b32_e32 v3, v0
	v_cmp_gt_i32_e32 vcc, 0, v0
	s_nop 1
	v_cndmask_b32_e32 v0, v2, v3, vcc
	ds_write2st64_b32 v48, v1, v0 offset1:65
	s_or_b64 exec, exec, s[4:5]
	v_add_u32_e32 v48, 0x200, v48
	v_add_u32_e32 v49, 0x80, v49
	s_add_u32 s2, s2, 1
	s_cmp_lt_u32 s2, s3
	s_cbranch_scc0 .LBB0_890
.Lsel_blk1:
	s_waitcnt vmcnt(6)
	v_mfma_f32_32x32x16_bf16 v[0:15], v[18:21], v[144:147], 0
	v_mfma_f32_32x32x16_bf16 v[0:15], v[22:25], v[148:151], v[0:15]
	v_min_u32_e32 v168, s7, v170
	v_lshlrev_b32_e32 v168, 6, v168
	v_lshl_add_u64 v[134:135], v[44:45], 0, v[168:169]
	global_load_dwordx4 v[144:147], v[134:135], off
	global_load_dwordx4 v[148:151], v[134:135], off offset:32
	v_add_u32_e32 v170, 0x80, v170
	v_cmp_gt_u32_e32 vcc, s72, v49
	s_nop 4
	s_and_saveexec_b64 s[4:5], vcc
	v_max_f32_e32 v0, 0, v0
	v_max_f32_e32 v8, 0, v8
	v_max_f32_e32 v1, 0, v1
	v_max_f32_e32 v9, 0, v9
	v_max_f32_e32 v2, 0, v2
	v_max_f32_e32 v10, 0, v10
	v_max_f32_e32 v3, 0, v3
	v_max_f32_e32 v11, 0, v11
	v_max_f32_e32 v4, 0, v4
	v_max_f32_e32 v12, 0, v12
	v_max_f32_e32 v5, 0, v5
	v_max_f32_e32 v13, 0, v13
	v_max_f32_e32 v6, 0, v6
	v_max_f32_e32 v14, 0, v14
	v_max_f32_e32 v7, 0, v7
	v_max_f32_e32 v15, 0, v15
	v_mul_f32_e32 v53, v38, v0
	v_mul_f32_e32 v52, v30, v8
	v_fmac_f32_e32 v53, v39, v1
	v_fmac_f32_e32 v52, v31, v9
	v_fmac_f32_e32 v53, v40, v2
	v_fmac_f32_e32 v52, v32, v10
	v_fmac_f32_e32 v53, v41, v3
	v_fmac_f32_e32 v52, v33, v11
	v_fmac_f32_e32 v53, v34, v4
	v_fmac_f32_e32 v52, v26, v12
	v_fmac_f32_e32 v53, v35, v5
	v_fmac_f32_e32 v52, v27, v13
	v_fmac_f32_e32 v53, v36, v6
	v_fmac_f32_e32 v52, v28, v14
	v_fma_f32 v1, v37, v7, v53
	v_fma_f32 v0, v29, v15, v52
	s_nop 0
	v_or_b32_e32 v2, 0x80000000, v1
	v_not_b32_e32 v3, v1
	v_cmp_gt_i32_e32 vcc, 0, v1
	s_nop 1
	v_cndmask_b32_e32 v1, v2, v3, vcc
	v_or_b32_e32 v2, 0x80000000, v0
	v_not_b32_e32 v3, v0
	v_cmp_gt_i32_e32 vcc, 0, v0
	s_nop 1
	v_cndmask_b32_e32 v0, v2, v3, vcc
	ds_write2st64_b32 v48, v1, v0 offset1:65
	s_or_b64 exec, exec, s[4:5]
	v_add_u32_e32 v48, 0x200, v48
	v_add_u32_e32 v49, 0x80, v49
	s_add_u32 s2, s2, 1
	s_cmp_lt_u32 s2, s3
	s_cbranch_scc0 .LBB0_890
.Lsel_blk2:
	s_waitcnt vmcnt(6)
	v_mfma_f32_32x32x16_bf16 v[0:15], v[18:21], v[152:155], 0
	v_mfma_f32_32x32x16_bf16 v[0:15], v[22:25], v[156:159], v[0:15]
	v_min_u32_e32 v168, s7, v170
	v_lshlrev_b32_e32 v168, 6, v168
	v_lshl_add_u64 v[134:135], v[44:45], 0, v[168:169]
	global_load_dwordx4 v[152:155], v[134:135], off
	global_load_dwordx4 v[156:159], v[134:135], off offset:32
	v_add_u32_e32 v170, 0x80, v170
	v_cmp_gt_u32_e32 vcc, s72, v49
	s_nop 4
	s_and_saveexec_b64 s[4:5], vcc
	v_max_f32_e32 v0, 0, v0
	v_max_f32_e32 v8, 0, v8
	v_max_f32_e32 v1, 0, v1
	v_max_f32_e32 v9, 0, v9
	v_max_f32_e32 v2, 0, v2
	v_max_f32_e32 v10, 0, v10
	v_max_f32_e32 v3, 0, v3
	v_max_f32_e32 v11, 0, v11
	v_max_f32_e32 v4, 0, v4
	v_max_f32_e32 v12, 0, v12
	v_max_f32_e32 v5, 0, v5
	v_max_f32_e32 v13, 0, v13
	v_max_f32_e32 v6, 0, v6
	v_max_f32_e32 v14, 0, v14
	v_max_f32_e32 v7, 0, v7
	v_max_f32_e32 v15, 0, v15
	v_mul_f32_e32 v53, v38, v0
	v_mul_f32_e32 v52, v30, v8
	v_fmac_f32_e32 v53, v39, v1
	v_fmac_f32_e32 v52, v31, v9
	v_fmac_f32_e32 v53, v40, v2
	v_fmac_f32_e32 v52, v32, v10
	v_fmac_f32_e32 v53, v41, v3
	v_fmac_f32_e32 v52, v33, v11
	v_fmac_f32_e32 v53, v34, v4
	v_fmac_f32_e32 v52, v26, v12
	v_fmac_f32_e32 v53, v35, v5
	v_fmac_f32_e32 v52, v27, v13
	v_fmac_f32_e32 v53, v36, v6
	v_fmac_f32_e32 v52, v28, v14
	v_fma_f32 v1, v37, v7, v53
	v_fma_f32 v0, v29, v15, v52
	s_nop 0
	v_or_b32_e32 v2, 0x80000000, v1
	v_not_b32_e32 v3, v1
	v_cmp_gt_i32_e32 vcc, 0, v1
	s_nop 1
	v_cndmask_b32_e32 v1, v2, v3, vcc
	v_or_b32_e32 v2, 0x80000000, v0
	v_not_b32_e32 v3, v0
	v_cmp_gt_i32_e32 vcc, 0, v0
	s_nop 1
	v_cndmask_b32_e32 v0, v2, v3, vcc
	ds_write2st64_b32 v48, v1, v0 offset1:65
	s_or_b64 exec, exec, s[4:5]
	v_add_u32_e32 v48, 0x200, v48
	v_add_u32_e32 v49, 0x80, v49
	s_add_u32 s2, s2, 1
	s_cmp_lt_u32 s2, s3
	s_cbranch_scc0 .LBB0_890
.Lsel_blk3:
	s_waitcnt vmcnt(6)
	v_mfma_f32_32x32x16_bf16 v[0:15], v[18:21], v[160:163], 0
	v_mfma_f32_32x32x16_bf16 v[0:15], v[22:25], v[164:167], v[0:15]
	v_min_u32_e32 v168, s7, v170
	v_lshlrev_b32_e32 v168, 6, v168
	v_lshl_add_u64 v[134:135], v[44:45], 0, v[168:169]
	global_load_dwordx4 v[160:163], v[134:135], off
	global_load_dwordx4 v[164:167], v[134:135], off offset:32
	v_add_u32_e32 v170, 0x80, v170
	v_cmp_gt_u32_e32 vcc, s72, v49
	s_nop 4
	s_and_saveexec_b64 s[4:5], vcc
	v_max_f32_e32 v0, 0, v0
	v_max_f32_e32 v8, 0, v8
	v_max_f32_e32 v1, 0, v1
	v_max_f32_e32 v9, 0, v9
	v_max_f32_e32 v2, 0, v2
	v_max_f32_e32 v10, 0, v10
	v_max_f32_e32 v3, 0, v3
	v_max_f32_e32 v11, 0, v11
	v_max_f32_e32 v4, 0, v4
	v_max_f32_e32 v12, 0, v12
	v_max_f32_e32 v5, 0, v5
	v_max_f32_e32 v13, 0, v13
	v_max_f32_e32 v6, 0, v6
	v_max_f32_e32 v14, 0, v14
	v_max_f32_e32 v7, 0, v7
	v_max_f32_e32 v15, 0, v15
	v_mul_f32_e32 v53, v38, v0
	v_mul_f32_e32 v52, v30, v8
	v_fmac_f32_e32 v53, v39, v1
	v_fmac_f32_e32 v52, v31, v9
	v_fmac_f32_e32 v53, v40, v2
	v_fmac_f32_e32 v52, v32, v10
	v_fmac_f32_e32 v53, v41, v3
	v_fmac_f32_e32 v52, v33, v11
	v_fmac_f32_e32 v53, v34, v4
	v_fmac_f32_e32 v52, v26, v12
	v_fmac_f32_e32 v53, v35, v5
	v_fmac_f32_e32 v52, v27, v13
	v_fmac_f32_e32 v53, v36, v6
	v_fmac_f32_e32 v52, v28, v14
	v_fma_f32 v1, v37, v7, v53
	v_fma_f32 v0, v29, v15, v52
	s_nop 0
	v_or_b32_e32 v2, 0x80000000, v1
	v_not_b32_e32 v3, v1
	v_cmp_gt_i32_e32 vcc, 0, v1
	s_nop 1
	v_cndmask_b32_e32 v1, v2, v3, vcc
	v_or_b32_e32 v2, 0x80000000, v0
	v_not_b32_e32 v3, v0
	v_cmp_gt_i32_e32 vcc, 0, v0
	s_nop 1
	v_cndmask_b32_e32 v0, v2, v3, vcc
	ds_write2st64_b32 v48, v1, v0 offset1:65
	s_or_b64 exec, exec, s[4:5]
	v_add_u32_e32 v48, 0x200, v48
	v_add_u32_e32 v49, 0x80, v49
	s_add_u32 s2, s2, 1
	s_cmp_lt_u32 s2, s3
	s_cbranch_scc1 .Lsel_blk0
